# e22: first grid barrier - the 16 per-XCD counter loads of a poll round issued together instead of serialized
# baseline (speedup 1.0000x reference)
; __device__ __forceinline__ unsigned xb_ld(unsigned* p)              { return __hip_atomic_load(p, __ATOMIC_RELAXED, __HIP_MEMORY_SCOPE_AGENT); }
; __device__ __forceinline__ void xcd_barrier_complete(unsigned* bar, unsigned x, unsigned& nloc, unsigned& nx) {
;     const unsigned G = gridDim.x * gridDim.y * gridDim.z;
;     unsigned sum, cnt, mine, sp = 0u;
;     for (;;) {
;         sum = 0u; cnt = 0u; mine = 0u;
; #pragma unroll
;         for (unsigned j = 0; j < 16; ++j) { const unsigned c = xb_ld(&bar[XB_XCNT(j)]); sum += c; cnt += (c > 0u) ? 1u : 0u; mine = (j == x) ? c : mine; }
;         if (sum == G) break;
;         __builtin_amdgcn_s_sleep(1);
;         if ((++sp & 255u) == 0u) { if (xb_ld(&bar[XB_TMO])) break; if (sp > XB_SPIN_CAP) { atomicAdd(&bar[XB_TMO], 1u); break; } }
;     }
.LBB0_144:
	global_load_dword v4, v3, s[82:83] sc1
	global_load_dword v2, v3, s[84:85] sc1
	s_mov_b64 s[12:13], -1
	v_readlane_b32 s2, v254, 6
	v_readlane_b32 s3, v254, 7
	s_nop 4
	global_load_dword v5, v3, s[2:3] sc1
	v_readlane_b32 s2, v254, 8
	v_readlane_b32 s3, v254, 9
	s_nop 4
	global_load_dword v6, v3, s[2:3] sc1
	v_readlane_b32 s2, v254, 10
	v_readlane_b32 s3, v254, 11
	s_nop 4
	global_load_dword v7, v3, s[2:3] sc1
	v_readlane_b32 s2, v254, 12
	v_readlane_b32 s3, v254, 13
	s_nop 4
	global_load_dword v8, v3, s[2:3] sc1
	v_readlane_b32 s2, v254, 14
	v_readlane_b32 s3, v254, 15
	s_nop 4
	global_load_dword v9, v3, s[2:3] sc1
	v_readlane_b32 s2, v254, 16
	v_readlane_b32 s3, v254, 17
	s_nop 4
	global_load_dword v10, v3, s[2:3] sc1
	v_readlane_b32 s2, v254, 18
	v_readlane_b32 s3, v254, 19
	s_nop 4
	global_load_dword v11, v3, s[2:3] sc1
	v_readlane_b32 s2, v254, 20
	v_readlane_b32 s3, v254, 21
	s_nop 4
	global_load_dword v12, v3, s[2:3] sc1
	v_readlane_b32 s2, v254, 22
	v_readlane_b32 s3, v254, 23
	s_nop 4
	global_load_dword v13, v3, s[2:3] sc1
	v_readlane_b32 s2, v254, 24
	v_readlane_b32 s3, v254, 25
	s_nop 4
	global_load_dword v14, v3, s[2:3] sc1
	v_readlane_b32 s2, v254, 26
	v_readlane_b32 s3, v254, 27
	s_nop 4
	global_load_dword v15, v3, s[2:3] sc1
	v_readlane_b32 s2, v254, 28
	v_readlane_b32 s3, v254, 29
	s_nop 4
	global_load_dword v16, v3, s[2:3] sc1
	v_readlane_b32 s2, v254, 30
	v_readlane_b32 s3, v254, 31
	s_nop 4
	global_load_dword v17, v3, s[2:3] sc1
	v_readlane_b32 s2, v254, 32
	v_readlane_b32 s3, v254, 33
	s_nop 4
	global_load_dword v18, v3, s[2:3] sc1
	s_mov_b64 s[2:3], -1
	s_waitcnt vmcnt(0)
	v_add_u32_e32 v19, v2, v4
	v_add_u32_e32 v19, v19, v5
	v_add_u32_e32 v19, v19, v6
	v_add_u32_e32 v19, v19, v7
	v_add_u32_e32 v19, v19, v8
	v_add_u32_e32 v19, v19, v9
	v_add_u32_e32 v19, v19, v10
	v_add_u32_e32 v19, v19, v11
	v_add_u32_e32 v19, v19, v12
	v_add_u32_e32 v19, v19, v13
	v_add_u32_e32 v19, v19, v14
	v_add_u32_e32 v19, v19, v15
	v_add_u32_e32 v19, v19, v16
	v_add_u32_e32 v19, v19, v17
	v_add_u32_e32 v19, v19, v18
	v_cmp_eq_u32_e32 vcc, s4, v19
	s_cbranch_vccnz .LBB0_143
	s_and_b32 s2, s5, 0xff
	s_cmp_eq_u32 s2, 0
	s_mov_b64 s[2:3], -1
	s_mov_b64 s[18:19], -1
	s_sleep 1
	s_cbranch_scc1 .LBB0_148
	s_and_b64 vcc, exec, s[18:19]
	s_cbranch_vccz .LBB0_143
